# removed the full vmcnt(0) drains hipcc left in the K-loop preheaders of the w_out and final down GEMMs
# speedup vs baseline: 1.0039x; 1.0015x over previous
;     __device__ bool next(int i, Unit& u) const { const int idx = i * G + c; if (idx >= 64) return false; u.kp = idx & 3; u.pn = (idx >> 2) & 7; u.pm = 192 + (idx >> 5); return true; }
; #define PG8_STAGE(bufoff, gbase, voff) do { _Pragma("unroll") for (int _i = 0; _i < 2; ++_i) \
;         __builtin_amdgcn_global_load_lds((const unsigned*)((const char*)(gbase) + (voff)[_i]), (LAS unsigned*)(lds + (bufoff) + ldsw + _i * 8192), 16, 0, 0); } while (0)
; #define PG8_LDA(dst, b, h) do { _Pragma("unroll") for (int m = 0; m < 4; ++m) _Pragma("unroll") for (int k = 0; k < 2; ++k) dst[m][k] = *(const LAS bf16x8*)(lds + PG8_SA(b, h) + aoff + m * 2048 + k * 1024); } while (0)
; #define PG8_LDB(dst, b, h) do { _Pragma("unroll") for (int n = 0; n < 2; ++n) _Pragma("unroll") for (int k = 0; k < 2; ++k) dst[n][k] = *(const LAS bf16x8*)(lds + PG8_SB(b, h) + boff + n * 2048 + k * 1024); } while (0)
; #define PG8_SCHED __builtin_amdgcn_sched_barrier(0)
; template <class Epi, class Sched = StaticOrder, bool ALIGN_EPI = true>
; __device__ __forceinline__ void gemm_phase(LAS unsigned char* lds, const Gemm g, const Sched& S, const Epi& E) {
;     ...
;         const bool has_next = S.next(ui + 1, nxt);
;         const char* nA = has_next ? (const char*)g.A + (size_t)nxt.pm * tstep + (size_t)nxt.kp * K * 2 : cA; const char* nB = has_next ? (const char*)g.Bt + (size_t)nxt.pn * tstep + (size_t)nxt.kp * K * 2 : cB;
;         for (int t = 0; t < nt; t += 2) {
;             const bool last = (t == nt - 2);
;             const char* a1 = cA + (size_t)(t + 1) * kstep;
;             const char* a2 = last ? nA : cA + (size_t)(t + 2) * kstep; const char* b2 = last ? nB : cB + (size_t)(t + 2) * kstep;
;             const char* a3 = a2 + kstep; const char* b3 = b2 + kstep;
;             PG8_LDB(B0, 0, 0); PG8_LDB(B1, 0, 1); PG8_SCHED; PG8_LDA(At, 0, 0); PG8_STAGE(PG8_SA(1, 1), a1 + hstep, voffA);
.LBB0_105:
	s_ashr_i32 s43, s42, 31
	s_lshl_b64 s[0:1], s[42:43], 20
	v_readlane_b32 s16, v253, 23
	v_readlane_b32 s17, v253, 24
	s_add_u32 s44, s16, s0
	s_addc_u32 s45, s17, s1
	s_and_b64 s[0:1], s[40:41], exec
	s_cselect_b32 s30, s45, s81
	s_cselect_b32 s31, s44, s80
	s_ashr_i32 s21, s20, 31
	s_lshl_b64 s[0:1], s[20:21], 20
	v_readlane_b32 s16, v253, 25
	s_add_u32 s0, s16, s0
	v_readlane_b32 s16, v253, 26
	s_addc_u32 s1, s16, s1
	s_and_b64 s[16:17], s[40:41], exec
	s_cselect_b32 s21, s1, s47
	s_cselect_b32 s36, s0, s46
	s_add_u32 s80, s80, 0x80080
	s_addc_u32 s81, s81, 0
	s_add_u32 s37, s46, 0x100
	s_addc_u32 s43, s47, 0
	s_mov_b32 s49, -2
	s_cmp_eq_u32 s22, 1
	s_cbranch_scc1 .Lmy_nb_106
	s_cmp_eq_u64 s[2:3], 0
	s_cbranch_scc1 .Lmy_nb_106
	s_barrier

;     __device__ bool next(int i, Unit& u) const { const int idx = i * G + c; if (idx >= 64) return false; u.kp = idx & 3; u.pn = (idx >> 2) & 7; u.pm = 192 + (idx >> 5); return true; }
; #define PG8_STAGE(bufoff, gbase, voff) do { _Pragma("unroll") for (int _i = 0; _i < 2; ++_i) \
;         __builtin_amdgcn_global_load_lds((const unsigned*)((const char*)(gbase) + (voff)[_i]), (LAS unsigned*)(lds + (bufoff) + ldsw + _i * 8192), 16, 0, 0); } while (0)
; #define PG8_LDA(dst, b, h) do { _Pragma("unroll") for (int m = 0; m < 4; ++m) _Pragma("unroll") for (int k = 0; k < 2; ++k) dst[m][k] = *(const LAS bf16x8*)(lds + PG8_SA(b, h) + aoff + m * 2048 + k * 1024); } while (0)
; #define PG8_LDB(dst, b, h) do { _Pragma("unroll") for (int n = 0; n < 2; ++n) _Pragma("unroll") for (int k = 0; k < 2; ++k) dst[n][k] = *(const LAS bf16x8*)(lds + PG8_SB(b, h) + boff + n * 2048 + k * 1024); } while (0)
; #define PG8_SCHED __builtin_amdgcn_sched_barrier(0)
; template <class Epi, class Sched = StaticOrder, bool ALIGN_EPI = true>
; __device__ __forceinline__ void gemm_phase(LAS unsigned char* lds, const Gemm g, const Sched& S, const Epi& E) {
;     ...
;         const bool has_next = S.next(ui + 1, nxt);
;         const char* nA = has_next ? (const char*)g.A + (size_t)nxt.pm * tstep + (size_t)nxt.kp * K * 2 : cA; const char* nB = has_next ? (const char*)g.Bt + (size_t)nxt.pn * tstep + (size_t)nxt.kp * K * 2 : cB;
;         for (int t = 0; t < nt; t += 2) {
;             const bool last = (t == nt - 2);
;             const char* a1 = cA + (size_t)(t + 1) * kstep;
;             const char* a2 = last ? nA : cA + (size_t)(t + 2) * kstep; const char* b2 = last ? nB : cB + (size_t)(t + 2) * kstep;
;             const char* a3 = a2 + kstep; const char* b3 = b2 + kstep;
;             PG8_LDB(B0, 0, 0); PG8_LDB(B1, 0, 1); PG8_SCHED; PG8_LDA(At, 0, 0); PG8_STAGE(PG8_SA(1, 1), a1 + hstep, voffA);
.LBB0_391:
	s_add_u32 s79, s0, 0x100
	s_addc_u32 s92, s1, 0
	s_mov_b32 s82, -2
	s_cmp_eq_u32 s22, 1
	s_cbranch_scc1 .Lmy_nb_392
	s_cmp_eq_u64 s[12:13], 0
	s_cbranch_scc1 .Lmy_nb_392
	s_barrier
